# attention LDS relayout (conflict-free swizzled K/V subtiles, b128 V reads, 5 DMA pieces/wave), counted lgkm waits, P0 rms gamma hoist, P4 latent-norm loads issued together
# speedup vs baseline: 1.0049x; 1.0049x over previous
; __device__ __forceinline__ unsigned pk2(float lo, float hi) { f32x2_t v = {lo, hi}; bf16x2_t b = __builtin_convertvector(v, bf16x2_t); return __builtin_bit_cast(unsigned, b); }
; __device__ __forceinline__ void rms_row2048(const float* xrow, const float* g, bf16_t* orow, int lane) {
;     const f32x4* xr = (const f32x4*)xrow + lane; const f32x4* gr = (const f32x4*)g + lane;
;     f32x4 v[8]; float s = 0.f;
; #pragma unroll
;     for (int j = 0; j < 8; ++j) { v[j] = xr[64 * j]; s += (v[j].x * v[j].x + v[j].y * v[j].y) + (v[j].z * v[j].z + v[j].w * v[j].w); }
;     const float r = rsqrtf(wave_sum(s) * (1.f / 2048.f) + EPS);
;     u32x2* o8 = (u32x2*)orow + lane;
; #pragma unroll
;     for (int j = 0; j < 8; ++j) { const f32x4 gg = gr[64 * j]; u32x2 w; w.x = pk2(v[j].x * r * gg.x, v[j].y * r * gg.y); w.y = pk2(v[j].z * r * gg.z, v[j].w * r * gg.w); o8[64 * j] = w; }
; __global__ void __launch_bounds__(512, 2) mega_fwd(Args args) {
;     ...
;         for (int m = gw; m < T; m += NGW) rms_row2048(x + (size_t)m * D, args.in[3], H + (size_t)m * D, lane);
.LBB0_257:
	s_or_b64 exec, exec, s[2:3]
	v_readlane_b32 s0, v238, 38
	s_cmpk_gt_i32 s0, 0x3fff
	v_readlane_b32 s1, v238, 39
	s_cbranch_scc1 .LBB0_260
	v_lshlrev_b32_e32 v0, 4, v184
	v_mov_b32_e32 v1, 0
	v_lshl_add_u64 v[16:17], s[58:59], 0, v[0:1]
	s_mov_b64 s[0:1], 0x1000
	v_lshl_add_u64 v[18:19], v[16:17], 0, s[0:1]
	s_mov_b64 s[0:1], 0x1400
	v_lshl_add_u64 v[20:21], v[16:17], 0, s[0:1]
	s_mov_b64 s[0:1], 0x1800
	v_lshl_add_u64 v[22:23], v[16:17], 0, s[0:1]
	v_readlane_b32 s0, v238, 38
	v_readlane_b32 s1, v238, 39
	s_mov_b32 s8, s0
	s_ashr_i32 s9, s0, 31
	s_lshl_b64 s[0:1], s[8:9], 12
	s_add_u32 s0, s86, s0
	v_lshlrev_b32_e32 v2, 3, v184
	v_mov_b32_e32 v3, v1
	s_addc_u32 s1, s87, s1
	v_lshl_add_u64 v[2:3], s[0:1], 0, v[2:3]
	s_mov_b64 s[0:1], 0x6800e00
	s_ashr_i32 s97, s96, 31
	v_lshl_add_u64 v[26:27], v[2:3], 0, s[0:1]
	s_lshl_b64 s[0:1], s[96:97], 12
	s_lshl_b64 s[4:5], s[8:9], 13
	s_add_u32 s4, s52, s4
	s_addc_u32 s5, s53, s5
	s_mov_b64 s[2:3], 0x1c00
	v_lshl_add_u64 v[0:1], s[4:5], 0, v[0:1]
	s_mov_b32 s6, s8
	v_lshl_add_u64 v[24:25], v[16:17], 0, s[2:3]
	v_lshl_add_u64 v[28:29], v[0:1], 0, s[2:3]
	s_lshl_b64 s[2:3], s[96:97], 13
	v_mov_b32_e32 v30, 0x358637bd
	s_mov_b32 s4, 0x800000
	v_writelane_b32 v238, s6, 38
	s_mov_b32 s5, s8
	s_nop 0
	v_writelane_b32 v238, s7, 39
	global_load_dwordx4 v[80:83], v[16:17], off
	global_load_dwordx4 v[84:87], v[16:17], off offset:1024
	global_load_dwordx4 v[88:91], v[16:17], off offset:2048
	global_load_dwordx4 v[92:95], v[16:17], off offset:3072
	global_load_dwordx4 v[96:99], v[18:19], off
	global_load_dwordx4 v[100:103], v[20:21], off
	global_load_dwordx4 v[104:107], v[22:23], off
	global_load_dwordx4 v[108:111], v[24:25], off
; __device__ __forceinline__ unsigned pk2(float lo, float hi) { f32x2_t v = {lo, hi}; bf16x2_t b = __builtin_convertvector(v, bf16x2_t); return __builtin_bit_cast(unsigned, b); }
; __device__ __forceinline__ void rms_row2048(const float* xrow, const float* g, bf16_t* orow, int lane) {
;     const f32x4* xr = (const f32x4*)xrow + lane; const f32x4* gr = (const f32x4*)g + lane;
;     f32x4 v[8]; float s = 0.f;
; #pragma unroll
;     for (int j = 0; j < 8; ++j) { v[j] = xr[64 * j]; s += (v[j].x * v[j].x + v[j].y * v[j].y) + (v[j].z * v[j].z + v[j].w * v[j].w); }
;     const float r = rsqrtf(wave_sum(s) * (1.f / 2048.f) + EPS);
;     u32x2* o8 = (u32x2*)orow + lane;
; #pragma unroll
;     for (int j = 0; j < 8; ++j) { const f32x4 gg = gr[64 * j]; u32x2 w; w.x = pk2(v[j].x * r * gg.x, v[j].y * r * gg.y); w.y = pk2(v[j].z * r * gg.z, v[j].w * r * gg.w); o8[64 * j] = w; }
; }
.LBB0_259:
	v_add_co_u32_e32 v0, vcc, 0xfffff000, v28
	global_load_dwordx4 v[4:7], v[28:29], off offset:-3072
	global_load_dwordx4 v[12:15], v[28:29], off offset:-2048
	global_load_dwordx4 v[8:11], v[28:29], off offset:-1024
	v_addc_co_u32_e32 v1, vcc, -1, v29, vcc
	global_load_dwordx4 v[32:35], v[0:1], off offset:-3072
	global_load_dwordx4 v[36:39], v[0:1], off offset:-2048
	global_load_dwordx4 v[40:43], v[0:1], off offset:-1024
	global_load_dwordx4 v[44:47], v[28:29], off offset:-4096
	s_nop 0
	global_load_dwordx4 v[0:3], v[28:29], off
	s_add_i32 s5, s5, s96
	s_cmpk_lt_i32 s5, 0x4000
	v_lshl_add_u64 v[28:29], v[28:29], 0, s[2:3]
	s_waitcnt vmcnt(0)
	v_mov_b32_e32 v68, v35
	v_pk_mul_f32 v[52:53], v[14:15], v[14:15]
	v_pk_mul_f32 v[54:55], v[12:13], v[12:13]
	v_mul_f32_e32 v56, v9, v9
	v_mul_f32_e32 v58, v11, v11
	v_mul_f32_e32 v64, v2, v2
	v_mul_f32_e32 v65, v3, v3
	v_pk_mov_b32 v[60:61], v[54:55], v[52:53] op_sel:[1,0]
	v_mov_b32_e32 v55, v53
	v_pk_fma_f32 v[52:53], v[8:9], v[8:9], v[56:57] op_sel_hi:[1,1,0]
	v_pk_fma_f32 v[56:57], v[10:11], v[10:11], v[58:59] op_sel_hi:[1,1,0]
	v_pk_mul_f32 v[62:63], v[42:43], v[42:43]
	v_pk_add_f32 v[54:55], v[60:61], v[54:55]
	v_pk_mul_f32 v[60:61], v[40:41], v[40:41]
	v_mov_b32_e32 v53, v64
	v_mov_b32_e32 v57, v65
	v_mov_b32_e32 v64, v33
	v_mov_b32_e32 v65, v37
	v_mov_b32_e32 v69, v39
	v_mov_b32_e32 v58, v32
	v_mov_b32_e32 v59, v36
	v_mov_b32_e32 v66, v34
	v_mov_b32_e32 v67, v38
	v_pk_mov_b32 v[74:75], v[60:61], v[62:63] op_sel:[1,0]
	v_mov_b32_e32 v61, v63
	v_pk_add_f32 v[52:53], v[52:53], v[56:57]
	v_pk_mul_f32 v[56:57], v[64:65], v[64:65]
	v_pk_mul_f32 v[62:63], v[68:69], v[68:69]
	v_pk_fma_f32 v[56:57], v[58:59], v[58:59], v[56:57]
	v_pk_fma_f32 v[58:59], v[66:67], v[66:67], v[62:63]
	v_mul_f32_e32 v71, v5, v5
	v_mul_f32_e32 v73, v6, v6
	v_mul_f32_e32 v70, v45, v45
	v_mul_f32_e32 v72, v47, v47
	v_pk_add_f32 v[60:61], v[74:75], v[60:61]
	v_pk_add_f32 v[56:57], v[56:57], v[58:59]
	v_mul_f32_e32 v31, v4, v4
	v_mul_f32_e32 v76, v7, v7
	v_pk_fma_f32 v[64:65], v[44:45], v[44:45], v[70:71] op_sel_hi:[1,1,0]
	v_pk_fma_f32 v[68:69], v[46:47], v[46:47], v[72:73] op_sel_hi:[1,1,0]
	v_pk_add_f32 v[58:59], v[60:61], v[60:61] op_sel:[0,1] op_sel_hi:[1,0]
	v_pk_add_f32 v[56:57], v[56:57], v[56:57] op_sel:[0,1] op_sel_hi:[1,0]
	v_mov_b32_e32 v65, v73
	v_mov_b32_e32 v69, v76
	v_mov_b32_e32 v59, v71
	v_mov_b32_e32 v57, v31
	v_pk_add_f32 v[60:61], v[64:65], v[68:69]
	v_pk_add_f32 v[56:57], v[56:57], v[58:59]
	v_mul_f32_e32 v77, v1, v1
	v_pk_add_f32 v[56:57], v[56:57], v[60:61]
	v_mul_f32_e32 v78, v0, v0
	v_pk_add_f32 v[54:55], v[54:55], v[54:55] op_sel:[0,1] op_sel_hi:[1,0]
	v_pk_add_f32 v[56:57], v[56:57], v[56:57] op_sel:[0,1] op_sel_hi:[1,0]
	v_mov_b32_e32 v55, v77
	v_mov_b32_e32 v57, v78
	v_pk_add_f32 v[54:55], v[56:57], v[54:55]
	s_nop 0
	v_pk_add_f32 v[52:53], v[54:55], v[52:53]
	s_nop 0
	v_add_f32_e32 v31, v52, v53
	s_nop 1
	v_add_f32_dpp v31, v31, v31 quad_perm:[1,0,3,2] row_mask:0xf bank_mask:0xf bound_ctrl:1
	s_nop 1
	v_add_f32_dpp v31, v31, v31 quad_perm:[2,3,0,1] row_mask:0xf bank_mask:0xf bound_ctrl:1
	s_nop 1
	v_add_f32_dpp v31, v31, v31 row_half_mirror row_mask:0xf bank_mask:0xf bound_ctrl:1
	s_nop 1
	v_add_f32_dpp v31, v31, v31 row_mirror row_mask:0xf bank_mask:0xf bound_ctrl:1
	s_nop 0
	v_readlane_b32 s8, v31, 16
	v_readlane_b32 s9, v31, 48
	v_readlane_b32 s6, v31, 0
	v_readlane_b32 s7, v31, 32
	v_mov_b32_e32 v52, s8
	v_mov_b32_e32 v53, s9
	v_pk_add_f32 v[52:53], s[6:7], v[52:53]
	s_nop 0
	v_add_f32_e32 v31, v52, v53
	v_fmamk_f32 v31, v31, 0x3a000000, v30
	v_mul_f32_e32 v52, 0x4b800000, v31
	v_cmp_gt_f32_e32 vcc, s4, v31
	s_nop 1
	v_cndmask_b32_e32 v31, v31, v52, vcc
	v_rsq_f32_e32 v31, v31
	s_nop 0
	v_mul_f32_e32 v52, 0x45800000, v31
	v_cndmask_b32_e32 v52, v31, v52, vcc
	v_pk_mul_f32 v[32:33], v[32:33], v[52:53] op_sel_hi:[1,0]
	v_pk_mul_f32 v[34:35], v[34:35], v[52:53] op_sel_hi:[1,0]
	v_pk_mul_f32 v[36:37], v[36:37], v[52:53] op_sel_hi:[1,0]
	v_pk_mul_f32 v[38:39], v[38:39], v[52:53] op_sel_hi:[1,0]
	v_pk_mul_f32 v[40:41], v[40:41], v[52:53] op_sel_hi:[1,0]
	v_pk_mul_f32 v[42:43], v[42:43], v[52:53] op_sel_hi:[1,0]
	v_pk_mul_f32 v[44:45], v[44:45], v[52:53] op_sel_hi:[1,0]
	v_pk_mul_f32 v[46:47], v[46:47], v[52:53] op_sel_hi:[1,0]
	v_pk_mul_f32 v[4:5], v[4:5], v[52:53] op_sel_hi:[1,0]
	v_pk_mul_f32 v[6:7], v[6:7], v[52:53] op_sel_hi:[1,0]
	v_pk_mul_f32 v[12:13], v[12:13], v[52:53] op_sel_hi:[1,0]
	v_pk_mul_f32 v[14:15], v[14:15], v[52:53] op_sel_hi:[1,0]
	v_pk_mul_f32 v[8:9], v[8:9], v[52:53] op_sel_hi:[1,0]
	v_pk_mul_f32 v[10:11], v[10:11], v[52:53] op_sel_hi:[1,0]
	v_pk_mul_f32 v[0:1], v[0:1], v[52:53] op_sel_hi:[1,0]
	v_pk_mul_f32 v[2:3], v[2:3], v[52:53] op_sel_hi:[1,0]
	v_pk_mul_f32 v[32:33], v[80:81], v[32:33]
	v_pk_mul_f32 v[34:35], v[82:83], v[34:35]
	v_pk_mul_f32 v[36:37], v[84:85], v[36:37]
	v_pk_mul_f32 v[38:39], v[86:87], v[38:39]
	v_pk_mul_f32 v[40:41], v[88:89], v[40:41]
	v_pk_mul_f32 v[42:43], v[90:91], v[42:43]
	v_pk_mul_f32 v[44:45], v[92:93], v[44:45]
	v_pk_mul_f32 v[46:47], v[94:95], v[46:47]
	v_pk_mul_f32 v[4:5], v[96:97], v[4:5]
	v_pk_mul_f32 v[6:7], v[98:99], v[6:7]
	v_pk_mul_f32 v[12:13], v[100:101], v[12:13]
	v_pk_mul_f32 v[14:15], v[102:103], v[14:15]
	v_pk_mul_f32 v[8:9], v[104:105], v[8:9]
	v_pk_mul_f32 v[10:11], v[106:107], v[10:11]
	v_pk_mul_f32 v[0:1], v[108:109], v[0:1]
	v_pk_mul_f32 v[2:3], v[110:111], v[2:3]
	v_cvt_pk_bf16_f32 v32, v32, v33
	v_cvt_pk_bf16_f32 v33, v34, v35
	v_cvt_pk_bf16_f32 v36, v36, v37
	v_cvt_pk_bf16_f32 v37, v38, v39
	v_cvt_pk_bf16_f32 v40, v40, v41
	v_cvt_pk_bf16_f32 v41, v42, v43
	v_cvt_pk_bf16_f32 v44, v44, v45
	v_cvt_pk_bf16_f32 v45, v46, v47
	v_cvt_pk_bf16_f32 v4, v4, v5
	v_cvt_pk_bf16_f32 v5, v6, v7
	v_cvt_pk_bf16_f32 v12, v12, v13
	v_cvt_pk_bf16_f32 v13, v14, v15
	v_cvt_pk_bf16_f32 v8, v8, v9
	v_cvt_pk_bf16_f32 v9, v10, v11
	v_cvt_pk_bf16_f32 v0, v0, v1
	v_cvt_pk_bf16_f32 v1, v2, v3
	global_store_dwordx2 v[26:27], v[32:33], off offset:-3584
	global_store_dwordx2 v[26:27], v[36:37], off offset:-3072
	global_store_dwordx2 v[26:27], v[40:41], off offset:-2560
	global_store_dwordx2 v[26:27], v[44:45], off offset:-2048
	global_store_dwordx2 v[26:27], v[4:5], off offset:-1536
	global_store_dwordx2 v[26:27], v[12:13], off offset:-1024
	global_store_dwordx2 v[26:27], v[8:9], off offset:-512
	global_store_dwordx2 v[26:27], v[0:1], off
	v_lshl_add_u64 v[26:27], v[26:27], 0, s[0:1]
	s_cbranch_scc1 .LBB0_259

; __device__ __forceinline__ unsigned pk2(float lo, float hi) { f32x2_t v = {lo, hi}; bf16x2_t b = __builtin_convertvector(v, bf16x2_t); return __builtin_bit_cast(unsigned, b); }
; __global__ void __launch_bounds__(512, 2) mega_fwd(Args args) {
;     ...
;         for (int m = gw; m < T; m += NGW) {
;             const bf16_t* zr = Z + (size_t)m * ZLD;
;             {
;                 const int h_ = lane >> 4, pc = lane & 15, fr_ = m & 15, fw_ = (m >> 4) & 3, ch_ = (m >> 6) & 31, b_ = m >> 11;
;                 const u32x4 gqv = *(const u32x4*)(zr + ZGQ + h_ * 128 + pc * 8);
;                 *(u32x4*)(H + ((((size_t)((b_ * 4 + h_) * 32 + ch_) * 4 + fw_) * 4 + (pc >> 2)) * 64 + (pc & 3) * 16 + fr_) * 8) = gqv;
;             }
;             {
;                 const u32x4 u = *(const u32x4*)(zr + ZQ + lane * 8);
;                 float v[8] = {bflo(u.x), bfhi(u.x), bflo(u.y), bfhi(u.y), bflo(u.z), bfhi(u.z), bflo(u.w), bfhi(u.w)};
;                 float sq = 0.f;
; #pragma unroll
;                 for (int e = 0; e < 8; ++e) sq += v[e] * v[e];
;                 const float r = rsqrtf(wave_sum(sq) * (1.f / 512.f) + EPS);
;                 const f32x4 g0 = *(const f32x4*)(args.in[9] + lane * 8), g1 = *(const f32x4*)(args.in[9] + lane * 8 + 4);
;                 u32x4 w; w.x = pk2(v[0] * r * g0.x, v[1] * r * g0.y); w.y = pk2(v[2] * r * g0.z, v[3] * r * g0.w); w.z = pk2(v[4] * r * g1.x, v[5] * r * g1.y); w.w = pk2(v[6] * r * g1.z, v[7] * r * g1.w);
;                 *(u32x4*)(QA + (size_t)m * 512 + lane * 8) = w;
;             }
;             {
;                 const u32x2 u = *(const u32x2*)(zr + ZKV + lane * 4);
;                 const float v0 = bflo(u.x), v1 = bfhi(u.x), v2 = bflo(u.y), v3 = bfhi(u.y);
;                 const float r = rsqrtf(wave_sum(v0 * v0 + v1 * v1 + v2 * v2 + v3 * v3) * (1.f / 256.f) + EPS);
;                 const f32x4 g0 = *(const f32x4*)(args.in[11] + lane * 4);
;                 u32x2 w; w.x = pk2(v0 * r * g0.x, v1 * r * g0.y); w.y = pk2(v2 * r * g0.z, v3 * r * g0.w);
;                 *(u32x2*)(KVA + (size_t)m * 256 + lane * 4) = w;
.LBB0_600:
	v_readlane_b32 s0, v238, 38
	s_cmpk_gt_i32 s0, 0x3fff
	v_readlane_b32 s1, v238, 39
	s_cbranch_scc1 .LBB0_603
	v_readlane_b32 s60, v238, 5
	v_readlane_b32 s62, v238, 7
	v_readlane_b32 s63, v238, 8
	v_mov_b32_e32 v17, 0
	v_lshlrev_b32_e32 v16, 5, v184
	v_readlane_b32 s66, v238, 11
	v_readlane_b32 s67, v238, 12
	v_readlane_b32 s70, v238, 15
	v_readlane_b32 s71, v238, 16
	s_mov_b64 s[2:3], s[62:63]
	v_readlane_b32 s0, v238, 38
	s_mov_b64 s[6:7], s[66:67]
	s_mov_b64 s[10:11], s[70:71]
	v_lshl_add_u64 v[4:5], s[2:3], 0, v[16:17]
	v_lshlrev_b32_e32 v16, 4, v184
	s_mov_b32 s12, s0
	v_and_b32_e32 v3, 15, v185
	v_lshlrev_b32_e32 v12, 3, v184
	v_lshl_add_u64 v[6:7], s[6:7], 0, v[16:17]
	v_readlane_b32 s1, v238, 39
	s_ashr_i32 s13, s0, 31
	s_mul_hi_i32 s6, s12, 0x1800
	s_mul_i32 s10, s12, 0x1800
	s_lshl_b64 s[0:1], s[12:13], 9
	v_or_b32_e32 v18, s10, v12
	v_mov_b32_e32 v19, s6
	s_mov_b64 s[6:7], 0xa800400
	v_and_b32_e32 v14, 0x300, v16
	v_lshlrev_b32_e32 v3, 4, v3
	v_or_b32_e32 v8, s0, v12
	s_lshl_b64 s[2:3], s[12:13], 10
	v_lshl_add_u64 v[12:13], v[18:19], 0, s[6:7]
	v_or3_b32 v18, s10, v14, v3
	s_mov_b64 s[8:9], 0xa800680
	v_lshlrev_b32_e32 v2, 4, v185
	v_mov_b32_e32 v9, s1
	s_mov_b64 s[0:1], 0x13800000
	s_ashr_i32 s97, s96, 31
	v_or_b32_e32 v10, s2, v16
	v_mov_b32_e32 v11, s3
	s_mov_b64 s[2:3], 0x12800000
	v_lshl_add_u64 v[14:15], v[18:19], 0, s[8:9]
	v_or_b32_e32 v18, s10, v16
	s_mov_b64 s[8:9], 0xa800000
	s_mov_b32 s10, s12
	v_lshrrev_b32_e32 v1, 4, v184
	v_bfe_u32 v0, v185, 2, 2
	v_and_b32_e32 v2, 48, v2
	v_readlane_b32 s61, v238, 6
	v_readlane_b32 s64, v238, 9
	v_readlane_b32 s65, v238, 10
	v_readlane_b32 s68, v238, 13
	v_readlane_b32 s69, v238, 14
	v_readlane_b32 s72, v238, 17
	v_readlane_b32 s73, v238, 18
	v_readlane_b32 s74, v238, 19
	v_readlane_b32 s75, v238, 20
	v_lshl_add_u64 v[8:9], v[8:9], 0, s[0:1]
	s_lshl_b64 s[0:1], s[96:97], 9
	v_lshl_add_u64 v[10:11], v[10:11], 0, s[2:3]
	s_lshl_b64 s[2:3], s[96:97], 10
	s_mul_hi_i32 s7, s96, 0x1800
	s_mul_i32 s6, s96, 0x1800
	v_lshl_add_u64 v[16:17], v[18:19], 0, s[8:9]
	v_mov_b32_e32 v3, 0x358637bd
	s_mov_b32 s8, 0x800000
	v_writelane_b32 v238, s10, 38
	s_mov_b32 s9, s12
	s_nop 0
	v_writelane_b32 v238, s11, 39
	global_load_dwordx4 v[60:63], v[4:5], off
	global_load_dwordx4 v[64:67], v[4:5], off offset:16
	global_load_dwordx4 v[68:71], v[6:7], off
; __device__ __forceinline__ unsigned pk2(float lo, float hi) { f32x2_t v = {lo, hi}; bf16x2_t b = __builtin_convertvector(v, bf16x2_t); return __builtin_bit_cast(unsigned, b); }
; __global__ void __launch_bounds__(512, 2) mega_fwd(Args args) {
;     ...
;             const bf16_t* zr = Z + (size_t)m * ZLD;
;             {
;                 const int h_ = lane >> 4, pc = lane & 15, fr_ = m & 15, fw_ = (m >> 4) & 3, ch_ = (m >> 6) & 31, b_ = m >> 11;
;                 const u32x4 gqv = *(const u32x4*)(zr + ZGQ + h_ * 128 + pc * 8);
;                 *(u32x4*)(H + ((((size_t)((b_ * 4 + h_) * 32 + ch_) * 4 + fw_) * 4 + (pc >> 2)) * 64 + (pc & 3) * 16 + fr_) * 8) = gqv;
;             }
;             {
;                 const u32x4 u = *(const u32x4*)(zr + ZQ + lane * 8);
;                 float v[8] = {bflo(u.x), bfhi(u.x), bflo(u.y), bfhi(u.y), bflo(u.z), bfhi(u.z), bflo(u.w), bfhi(u.w)};
;                 float sq = 0.f;
; #pragma unroll
;                 for (int e = 0; e < 8; ++e) sq += v[e] * v[e];
;                 const float r = rsqrtf(wave_sum(sq) * (1.f / 512.f) + EPS);
;                 const f32x4 g0 = *(const f32x4*)(args.in[9] + lane * 8), g1 = *(const f32x4*)(args.in[9] + lane * 8 + 4);
;                 u32x4 w; w.x = pk2(v[0] * r * g0.x, v[1] * r * g0.y); w.y = pk2(v[2] * r * g0.z, v[3] * r * g0.w); w.z = pk2(v[4] * r * g1.x, v[5] * r * g1.y); w.w = pk2(v[6] * r * g1.z, v[7] * r * g1.w);
;                 *(u32x4*)(QA + (size_t)m * 512 + lane * 8) = w;
;             }
;             {
;                 const u32x2 u = *(const u32x2*)(zr + ZKV + lane * 4);
;                 const float v0 = bflo(u.x), v1 = bfhi(u.x), v2 = bflo(u.y), v3 = bfhi(u.y);
;                 const float r = rsqrtf(wave_sum(v0 * v0 + v1 * v1 + v2 * v2 + v3 * v3) * (1.f / 256.f) + EPS);
;                 const f32x4 g0 = *(const f32x4*)(args.in[11] + lane * 4);
;                 u32x2 w; w.x = pk2(v0 * r * g0.x, v1 * r * g0.y); w.y = pk2(v2 * r * g0.z, v3 * r * g0.w);
;                 *(u32x2*)(KVA + (size_t)m * 256 + lane * 4) = w;
;             }
.LBB0_602:
	v_lshl_add_u64 v[18:19], s[86:87], 0, v[14:15]
	v_lshl_add_u64 v[22:23], s[86:87], 0, v[16:17]
	v_lshl_add_u64 v[32:33], s[86:87], 0, v[12:13]
	global_load_dwordx4 v[52:55], v[18:19], off
	global_load_dwordx4 v[46:49], v[22:23], off
	global_load_dwordx2 v[50:51], v[32:33], off
	s_ashr_i32 s11, s9, 9
	s_and_b32 s11, s11, 0x7fffffc
	s_bfe_u32 s10, s9, 0x50006
	v_or_b32_e32 v24, s11, v1
	v_lshl_or_b32 v24, v24, 5, s10
	v_ashrrev_i32_e32 v25, 31, v24
	s_lshr_b32 s12, s9, 2
	v_lshlrev_b64 v[24:25], 4, v[24:25]
	v_and_or_b32 v24, s12, 12, v24
	v_or_b32_e32 v24, v24, v0
	v_lshlrev_b64 v[24:25], 6, v[24:25]
	v_or_b32_e32 v24, v24, v2
	v_and_or_b32 v24, s9, 15, v24
	v_lshl_add_u64 v[24:25], v[24:25], 4, s[40:41]
	v_lshl_add_u64 v[30:31], s[86:87], 0, v[10:11]
	s_add_i32 s9, s9, s96
	v_lshl_add_u64 v[10:11], v[10:11], 0, s[2:3]
	v_lshl_add_u64 v[12:13], v[12:13], 0, s[6:7]
	v_lshl_add_u64 v[14:15], v[14:15], 0, s[6:7]
	v_lshl_add_u64 v[16:17], v[16:17], 0, s[6:7]
	s_cmpk_gt_i32 s9, 0x3fff
	s_waitcnt vmcnt(2)
	global_store_dwordx4 v[24:25], v[52:55], off
	s_waitcnt vmcnt(2)
	v_lshlrev_b32_e32 v38, 16, v46
	v_and_b32_e32 v39, 0xffff0000, v46
	v_lshlrev_b32_e32 v34, 16, v49
	v_and_b32_e32 v35, 0xffff0000, v49
	v_lshlrev_b32_e32 v36, 16, v48
	v_and_b32_e32 v37, 0xffff0000, v48
	v_lshlrev_b32_e32 v20, 16, v47
	v_and_b32_e32 v21, 0xffff0000, v47
	v_pk_mul_f32 v[44:45], v[38:39], v[38:39]
	v_pk_mul_f32 v[42:43], v[20:21], v[20:21]
	v_add_f32_e32 v44, v44, v45
	v_add_f32_e32 v42, v44, v42
	v_pk_mul_f32 v[40:41], v[36:37], v[36:37]
	v_add_f32_e32 v42, v42, v43
	v_add_f32_e32 v40, v42, v40
	v_pk_mul_f32 v[18:19], v[34:35], v[34:35]
	v_add_f32_e32 v40, v40, v41
	v_add_f32_e32 v18, v40, v18
	v_add_f32_e32 v18, v18, v19
	s_nop 1
	v_add_f32_dpp v18, v18, v18 quad_perm:[1,0,3,2] row_mask:0xf bank_mask:0xf bound_ctrl:1
	s_nop 1
	v_add_f32_dpp v18, v18, v18 quad_perm:[2,3,0,1] row_mask:0xf bank_mask:0xf bound_ctrl:1
	s_nop 1
	v_add_f32_dpp v18, v18, v18 row_half_mirror row_mask:0xf bank_mask:0xf bound_ctrl:1
	s_nop 1
	v_add_f32_dpp v18, v18, v18 row_mirror row_mask:0xf bank_mask:0xf bound_ctrl:1
	s_nop 0
	v_readlane_b32 s12, v18, 16
	v_readlane_b32 s13, v18, 48
	v_readlane_b32 s10, v18, 0
	v_readlane_b32 s11, v18, 32
	v_mov_b32_e32 v18, s12
	v_mov_b32_e32 v19, s13
	v_pk_add_f32 v[18:19], s[10:11], v[18:19]
	s_nop 0
	v_add_f32_e32 v18, v18, v19
	v_fmamk_f32 v18, v18, 0x3b000000, v3
	v_mul_f32_e32 v19, 0x4b800000, v18
	v_cmp_gt_f32_e32 vcc, s8, v18
	s_nop 1
	v_cndmask_b32_e32 v18, v18, v19, vcc
	v_rsq_f32_e32 v18, v18
	s_nop 0
	v_mul_f32_e32 v19, 0x45800000, v18
	v_cndmask_b32_e32 v18, v18, v19, vcc
	v_pk_mul_f32 v[38:39], v[18:19], v[38:39] op_sel_hi:[0,1]
	v_pk_mul_f32 v[20:21], v[18:19], v[20:21] op_sel_hi:[0,1]
	v_pk_mul_f32 v[36:37], v[18:19], v[36:37] op_sel_hi:[0,1]
	v_pk_mul_f32 v[18:19], v[18:19], v[34:35] op_sel_hi:[0,1]
	v_pk_mul_f32 v[22:23], v[60:61], v[38:39]
	v_pk_mul_f32 v[20:21], v[62:63], v[20:21]
	v_pk_mul_f32 v[24:25], v[64:65], v[36:37]
	v_pk_mul_f32 v[26:27], v[66:67], v[18:19]
	v_cvt_pk_bf16_f32 v18, v22, v23
	v_cvt_pk_bf16_f32 v19, v20, v21
	v_cvt_pk_bf16_f32 v20, v24, v25
	v_cvt_pk_bf16_f32 v21, v26, v27
	global_store_dwordx4 v[30:31], v[18:21], off
	v_lshl_add_u64 v[24:25], s[86:87], 0, v[8:9]
	v_lshl_add_u64 v[8:9], v[8:9], 0, s[0:1]
	s_waitcnt vmcnt(2)
	v_lshlrev_b32_e32 v28, 16, v50
	v_and_b32_e32 v29, 0xffff0000, v50
	v_lshlrev_b32_e32 v26, 16, v51
	v_and_b32_e32 v27, 0xffff0000, v51
	v_pk_mul_f32 v[30:31], v[28:29], v[28:29]
	v_pk_mul_f32 v[22:23], v[26:27], v[26:27]
	v_add_f32_e32 v30, v30, v31
	v_add_f32_e32 v22, v22, v30
	v_add_f32_e32 v22, v23, v22
	s_nop 1
	v_add_f32_dpp v22, v22, v22 quad_perm:[1,0,3,2] row_mask:0xf bank_mask:0xf bound_ctrl:1
	s_nop 1
	v_add_f32_dpp v22, v22, v22 quad_perm:[2,3,0,1] row_mask:0xf bank_mask:0xf bound_ctrl:1
	s_nop 1
	v_add_f32_dpp v22, v22, v22 row_half_mirror row_mask:0xf bank_mask:0xf bound_ctrl:1
	s_nop 1
	v_add_f32_dpp v22, v22, v22 row_mirror row_mask:0xf bank_mask:0xf bound_ctrl:1
	s_nop 0
	v_readlane_b32 s12, v22, 16
	v_readlane_b32 s13, v22, 48
	v_readlane_b32 s10, v22, 0
	v_readlane_b32 s11, v22, 32
	v_mov_b32_e32 v22, s12
	v_mov_b32_e32 v23, s13
	v_pk_add_f32 v[22:23], s[10:11], v[22:23]
	s_nop 0
	v_add_f32_e32 v22, v22, v23
	v_fmamk_f32 v22, v22, 0x3b800000, v3
	v_mul_f32_e32 v23, 0x4b800000, v22
	v_cmp_gt_f32_e32 vcc, s8, v22
	s_nop 1
	v_cndmask_b32_e32 v22, v22, v23, vcc
	v_rsq_f32_e32 v22, v22
	s_nop 0
	v_mul_f32_e32 v23, 0x45800000, v22
	v_cndmask_b32_e32 v22, v22, v23, vcc
	v_pk_mul_f32 v[28:29], v[22:23], v[28:29] op_sel_hi:[0,1]
	v_pk_mul_f32 v[22:23], v[22:23], v[26:27] op_sel_hi:[0,1]
	v_pk_mul_f32 v[18:19], v[68:69], v[28:29]
	v_pk_mul_f32 v[20:21], v[70:71], v[22:23]
	v_cvt_pk_bf16_f32 v18, v18, v19
	v_cvt_pk_bf16_f32 v19, v20, v21
	global_store_dwordx2 v[24:25], v[18:19], off
	s_cbranch_scc0 .LBB0_602

; #define AT_DMA(t_, slot_) do { _Pragma("unroll") for (int j = 0; j < NJ; ++j) { const int g = wid + 8 * j; if (g < NIT) { \
;         const bf16_t* src_ = (g < NKI) ? (Kp + (size_t)(t_) * 64 * ldk + goff[j]) : (VTp + (size_t)(t_) * 64 + goff[j]); \
;         __builtin_amdgcn_global_load_lds((const unsigned*)src_, (LAS unsigned*)(lds + (slot_) * BUF + g * 1024), 16, 0, 0); } } } while (0)
; #define AT_WAIT_KEEP1() do { if (full) asm volatile("s_waitcnt vmcnt(%0)" :: "n"(NJ) : "memory"); else asm volatile("s_waitcnt vmcnt(%0)" :: "n"(NJ - 1) : "memory"); } while (0)
; #define AT_WAIT_ALL() asm volatile("s_waitcnt vmcnt(0)" ::: "memory")
; template <int DQK, int QF>
; __device__ __forceinline__ void attn_unit_dma(LAS unsigned char* lds, const bf16_t* Qp, int ldq, const bf16_t* Kp, int ldk, const bf16_t* VTp, int ldvt, bf16_t* Op, int ldo, int nkt, int wave_last, const float* qgam, float qscale) {
;     ...
;     asm volatile("s_waitcnt vmcnt(0)" ::: "memory");
;     AT_DMA(0, 0);
;     if (nkt > 1) { AT_DMA(1, 1); AT_WAIT_KEEP1(); } else AT_WAIT_ALL();
.LBB0_1080:
	s_lshl_b32 s12, s23, 10
	s_add_i32 m0, s12, 0
	s_and_b64 s[12:13], exec, s[50:51]
	s_cselect_b32 s13, s83, s27
	s_cselect_b32 s12, s82, s26
	v_lshlrev_b32_e32 v49, 1, v48
.LBB0_1081:
	s_add_i32 s34, s16, 32
	v_lshl_add_u32 v49, s34, 6, v213
	v_mul_hi_u32 v50, v49, s75
	v_lshrrev_b32_e32 v50, 1, v50
	v_lshl_add_u32 v51, v50, 3, v50
	v_sub_u32_e32 v51, v49, v51
	v_lshlrev_b32_e32 v49, 14, v50
	v_lshlrev_b32_e32 v50, 3, v51
	v_cmp_ne_u32_e32 vcc, 8, v51
	s_cmpk_lt_u32 s33, 0x2c0
	s_cselect_b64 s[60:61], -1, 0
	v_cndmask_b32_e32 v54, 56, v50, vcc
	s_cmpk_gt_u32 s33, 0x2bf
	v_or_b32_e32 v52, v54, v49
	s_cbranch_scc1 .LBB0_1083
	s_lshl_b32 s12, s34, 10
	v_mov_b32_e32 v53, v189
	s_add_i32 m0, s12, 0
	v_lshl_add_u64 v[50:51], v[52:53], 1, s[26:27]
.LBB0_1083:
	s_add_i32 s35, s16, 40
	v_lshl_add_u32 v50, s35, 6, v213
	v_mul_hi_u32 v51, v50, s75
	v_lshrrev_b32_e32 v51, 1, v51
	v_lshl_add_u32 v53, v51, 3, v51
	v_sub_u32_e32 v50, v50, v53
	s_cmpk_lt_u32 s33, 0xc0
	v_lshlrev_b32_e32 v55, 14, v51
	v_lshlrev_b32_e32 v51, 3, v50
	v_cmp_ne_u32_e32 vcc, 8, v50
	s_cselect_b64 s[62:63], -1, 0
	s_cmpk_gt_u32 s33, 0xbf
	v_cndmask_b32_e32 v56, 56, v51, vcc
	s_cselect_b64 s[64:65], -1, 0
	v_or_b32_e32 v50, v56, v55
	s_and_b64 vcc, exec, s[64:65]
	s_cbranch_vccnz .LBB0_1085
	s_lshl_b32 s12, s35, 10
	v_mov_b32_e32 v51, v189
	s_add_i32 m0, s12, 0
	v_lshl_add_u64 v[58:59], v[50:51], 1, s[26:27]
.LBB0_1085:
	s_cmp_gt_i32 s0, -1
	s_cselect_b64 s[12:13], -1, 0
	s_cmp_lt_i32 s0, 0
	s_mov_b64 s[66:67], -1
	s_cbranch_scc0 .LBB0_1087
	s_waitcnt vmcnt(0)
	s_mov_b64 s[66:67], 0

; #define AT_DMA(t_, slot_) do { _Pragma("unroll") for (int j = 0; j < NJ; ++j) { const int g = wid + 8 * j; if (g < NIT) { \
;         const bf16_t* src_ = (g < NKI) ? (Kp + (size_t)(t_) * 64 * ldk + goff[j]) : (VTp + (size_t)(t_) * 64 + goff[j]); \
;         __builtin_amdgcn_global_load_lds((const unsigned*)src_, (LAS unsigned*)(lds + (slot_) * BUF + g * 1024), 16, 0, 0); } } } while (0)
; #define AT_WAIT_KEEP1() do { if (full) asm volatile("s_waitcnt vmcnt(%0)" :: "n"(NJ) : "memory"); else asm volatile("s_waitcnt vmcnt(%0)" :: "n"(NJ - 1) : "memory"); } while (0)
; #define AT_WAIT_ALL() asm volatile("s_waitcnt vmcnt(0)" ::: "memory")
; template <int DQK, int QF>
; __device__ __forceinline__ void attn_unit_dma(LAS unsigned char* lds, const bf16_t* Qp, int ldq, const bf16_t* Kp, int ldk, const bf16_t* VTp, int ldvt, bf16_t* Op, int ldo, int nkt, int wave_last, const float* qgam, float qscale) {
;     ...
;     constexpr int NKI = KBYTES / 1024, NVI = VBYTES / 1024, NIT = NKI + NVI, NJ = (NIT + 7) / 8, KCH = KROW / 16, VCH = VROW / 16;
;     static_assert(KBYTES % 1024 == 0 && VBYTES % 1024 == 0, "slot image is whole 1 KiB pieces");
;     int goff[NJ];
; #pragma unroll
;     for (int j = 0; j < NJ; ++j) {
;         const int g = wid + 8 * j;
;         if (g < NKI) { const int q = g * 64 + lane; int row = q / KCH, cc = q % KCH; if (cc == KCH - 1) cc = KCH - 2; goff[j] = row * ldk + cc * 8; }
;         else { const int q = (g - NKI) * 64 + lane; int row = q / VCH, cc = q % VCH; if (cc == VCH - 1) cc = VCH - 2; goff[j] = row * ldvt + cc * 8; }
;     }
;     const bool full = (wid + 8 * (NJ - 1)) < NIT;
;     ...
;     asm volatile("s_waitcnt vmcnt(0)" ::: "memory");
;     AT_DMA(0, 0);
;     if (nkt > 1) { AT_DMA(1, 1); AT_WAIT_KEEP1(); } else AT_WAIT_ALL();
;     __builtin_amdgcn_s_barrier();
;     int slot = 0;
.LBB0_1095:
	s_lshl_b32 s33, s35, 10
	v_mov_b32_e32 v51, v189
	s_add_i32 s33, s33, 0
	v_lshl_add_u64 v[50:51], v[50:51], 1, s[26:27]
	s_add_i32 m0, s33, 0xac00
	v_lshl_add_u64 v[50:51], v[50:51], 0, s[4:5]
	s_waitcnt vmcnt(6)
.LBB0_1096:
	v_lshrrev_b32_e32 v206, 2, v184
	v_and_b32_e32 v207, 3, v184
	v_lshrrev_b32_e32 v199, 4, v184
	v_and_b32_e32 v199, 2, v199
	v_xor_b32_e32 v207, v207, v199
	v_lshrrev_b32_e32 v199, 2, v206
	v_and_b32_e32 v208, 3, v206
	v_lshl_add_u32 v199, v199, 3, v208
	s_and_b32 s33, s16, 3
	s_lshr_b32 s84, s33, 1
	s_lshl_b32 s84, s84, 5
	s_and_b32 s33, s33, 1
	s_lshl_b32 s33, s33, 2
	s_add_i32 s33, s33, s84
	v_add_u32_e32 v199, s33, v199
	v_mul_u32_u24_e32 v199, 0xc00, v199
	v_lshl_add_u32 v199, v207, 4, v199
	s_lshr_b32 s33, s16, 2
	s_lshl_b32 s33, s33, 6
	v_add_u32_e32 v200, s33, v199
	s_lshl_b32 s33, s16, 4
	v_add_u32_e32 v199, s33, v206
	v_lshlrev_b32_e32 v199, 15, v199
	v_lshl_add_u32 v202, v207, 4, v199
	v_and_b32_e32 v206, 15, v184
	v_lshrrev_b32_e32 v207, 4, v184
	v_lshlrev_b32_e32 v204, 6, v206
	v_lshl_add_u32 v204, v207, 4, v204
	v_lshrrev_b32_e32 v206, 3, v206
	v_lshlrev_b32_e32 v206, 5, v206
	v_xor_b32_e32 v204, v204, v206
	s_lshl_b32 s33, s16, 10
	s_mov_b32 m0, s33
	s_nop 0
	global_load_lds_dwordx4 v200, s[82:83]
	s_add_i32 m0, s33, 0x1f80
	s_nop 0
	global_load_lds_dwordx4 v200, s[82:83] offset:128
	s_add_i32 m0, s33, 0x3f00
	s_nop 0
	global_load_lds_dwordx4 v200, s[82:83] offset:256
	s_add_i32 m0, s33, 0x6000
	s_nop 0
	global_load_lds_dwordx4 v202, s[26:27]
	s_add_i32 m0, s33, 0x7fc0
	s_nop 0
	global_load_lds_dwordx4 v202, s[26:27] offset:64
	s_add_i32 s33, s33, 0xa000
	s_mov_b32 m0, s33
	s_nop 0
	global_load_lds_dwordx4 v200, s[92:93]
	s_add_i32 m0, s33, 0x1f80
	s_nop 0
	global_load_lds_dwordx4 v200, s[92:93] offset:128
	s_add_i32 m0, s33, 0x3f00
	s_nop 0
	global_load_lds_dwordx4 v200, s[92:93] offset:256
	s_add_i32 m0, s33, 0x6000
	s_nop 0
	global_load_lds_dwordx4 v202, s[90:91]
	s_add_i32 m0, s33, 0x7fc0
	s_nop 0
	global_load_lds_dwordx4 v202, s[90:91] offset:64
	s_waitcnt vmcnt(5)
	s_andn2_b64 vcc, exec, s[12:13]
	s_barrier
	s_cbranch_vccnz .LBB0_1060
	s_add_i32 s12, s14, s72
	s_ashr_i32 s13, s12, 31
	s_lshr_b32 s13, s13, 26
	v_add_u32_e32 v50, v54, v49
	v_mov_b32_e32 v51, v189
	s_lshl_b32 s0, s0, 2
	s_add_i32 s12, s12, s13
	v_lshl_add_u64 v[208:209], v[50:51], 1, s[36:37]
	v_add_u32_e32 v50, v56, v55
	v_mov_b32_e32 v56, 0
	s_add_i32 s0, s0, 4
	s_ashr_i32 s95, s12, 6
	v_mov_b32_e32 v201, v189
	s_lshl_b32 s97, s16, 10
	v_mov_b32_e32 v203, v189
	s_lshl_b32 s33, s17, 10
	v_mov_b32_e32 v205, v189
	s_lshl_b32 s16, s22, 10
	s_lshl_b32 s17, s23, 10
	s_lshl_b32 s22, s34, 10
	s_lshl_b32 s23, s35, 10
	v_lshl_add_u64 v[210:211], v[50:51], 1, s[36:37]
	s_mov_b32 s34, 0
	v_mov_b32_e32 v128, 0xf149f2ca
	v_lshlrev_b32_e32 v199, 1, v48
	s_mov_b64 s[66:67], s[36:37]
	s_mov_b64 s[68:69], s[28:29]
	v_mov_b32_e32 v112, 0xf149f2ca
	s_mov_b32 s35, 0
	v_mov_b32_e32 v57, v56
	v_mov_b32_e32 v58, v56
	v_mov_b32_e32 v59, v56
	v_mov_b32_e32 v60, v56
	v_mov_b32_e32 v61, v56
	v_mov_b32_e32 v62, v56
	v_mov_b32_e32 v63, v56
	v_mov_b32_e32 v64, v56
	v_mov_b32_e32 v65, v56
	v_mov_b32_e32 v66, v56
	v_mov_b32_e32 v67, v56
	v_mov_b32_e32 v68, v56
	v_mov_b32_e32 v69, v56
	v_mov_b32_e32 v70, v56
	v_mov_b32_e32 v71, v56
	v_mov_b32_e32 v48, v56
	v_mov_b32_e32 v49, v56
	v_mov_b32_e32 v50, v56
	v_mov_b32_e32 v51, v56
	v_mov_b32_e32 v108, v56
	v_mov_b32_e32 v109, v56
	v_mov_b32_e32 v110, v56
	v_mov_b32_e32 v111, v56
	v_mov_b32_e32 v104, v56
	v_mov_b32_e32 v105, v56
	v_mov_b32_e32 v106, v56
	v_mov_b32_e32 v107, v56
	v_mov_b32_e32 v88, v56
	v_mov_b32_e32 v89, v56
	v_mov_b32_e32 v90, v56
	v_mov_b32_e32 v91, v56
	v_mov_b32_e32 v84, v56
	v_mov_b32_e32 v85, v56
	v_mov_b32_e32 v86, v56
	v_mov_b32_e32 v87, v56
	v_mov_b32_e32 v92, v56
	v_mov_b32_e32 v93, v56
	v_mov_b32_e32 v94, v56
	v_mov_b32_e32 v95, v56
	v_mov_b32_e32 v100, v56
	v_mov_b32_e32 v101, v56
	v_mov_b32_e32 v102, v56
	v_mov_b32_e32 v103, v56
	v_mov_b32_e32 v96, v56
	v_mov_b32_e32 v97, v56
	v_mov_b32_e32 v98, v56
	v_mov_b32_e32 v99, v56
	v_mov_b32_e32 v72, v56
	v_mov_b32_e32 v73, v56
	v_mov_b32_e32 v74, v56
	v_mov_b32_e32 v75, v56
	v_mov_b32_e32 v76, v56
	v_mov_b32_e32 v77, v56
	v_mov_b32_e32 v78, v56
	v_mov_b32_e32 v79, v56
	v_mov_b32_e32 v80, v56
	v_mov_b32_e32 v81, v56
	v_mov_b32_e32 v82, v56
	v_mov_b32_e32 v83, v56
	v_mov_b32_e32 v52, v56
	v_mov_b32_e32 v53, v56
	v_mov_b32_e32 v54, v56
	v_mov_b32_e32 v55, v56
	v_mov_b32_e32 v206, v56
	v_mov_b32_e32 v207, v56
	s_waitcnt vmcnt(0)
	s_branch .LBB0_1099

; #define LAS __attribute__((address_space(3)))
; #define AT_DMA(t_, slot_) do { _Pragma("unroll") for (int j = 0; j < NJ; ++j) { const int g = wid + 8 * j; if (g < NIT) { \
;         const bf16_t* src_ = (g < NKI) ? (Kp + (size_t)(t_) * 64 * ldk + goff[j]) : (VTp + (size_t)(t_) * 64 + goff[j]); \
;         __builtin_amdgcn_global_load_lds((const unsigned*)src_, (LAS unsigned*)(lds + (slot_) * BUF + g * 1024), 16, 0, 0); } } } while (0)
; template <int DQK, int QF>
; __device__ __forceinline__ void attn_unit_dma(LAS unsigned char* lds, const bf16_t* Qp, int ldq, const bf16_t* Kp, int ldk, const bf16_t* VTp, int ldvt, bf16_t* Op, int ldo, int nkt, int wave_last, const float* qgam, float qscale) {
;     ...
;     for (int t = 0; t < nkt; ++t) {
;         const int s2slot = (slot == 0) ? 2 : slot - 1;
;         if (t + 2 < nkt) AT_DMA(t + 2, s2slot);
;         if (t <= wave_last) {
;             const LAS unsigned char* kb = lds + slot * BUF; const LAS unsigned char* vb = kb + KBYTES;
;             f32x4 st[QF][4];
; #pragma unroll
;             for (int qf = 0; qf < QF; ++qf)
; #pragma unroll
;                 for (int m = 0; m < 4; ++m) st[qf][m] = (f32x4){0.f, 0.f, 0.f, 0.f};
;             {
;                 bf16x8 kf[2][4];
; #pragma unroll
;                 for (int m = 0; m < 4; ++m) kf[0][m] = *(const LAS bf16x8*)(kb + (16 * m + fr) * KROW + fq * 16);
; #pragma unroll
;                 for (int s = 0; s < KS; ++s) {
;                     if (s + 1 < KS) {
; #pragma unroll
;                         for (int m = 0; m < 4; ++m) kf[(s + 1) & 1][m] = *(const LAS bf16x8*)(kb + (16 * m + fr) * KROW + (s + 1) * 64 + fq * 16);
;                     }
;                     __builtin_amdgcn_sched_group_barrier(0x100, 4, 0);
;                     __builtin_amdgcn_sched_group_barrier(0x008, 4 * QF, 0);
; #pragma unroll
;                     for (int m = 0; m < 4; ++m)
; #pragma unroll
;                         for (int qf = 0; qf < QF; ++qf) st[qf][m] = __builtin_amdgcn_mfma_f32_16x16x32_bf16(kf[s & 1][m], qreg[qf][s], st[qf][m], 0, 0, 0);
;                 }
.LBB0_1099:
	s_add_i32 s12, s35, 2
	s_cmp_ge_i32 s12, s0
	s_cselect_b64 s[70:71], -1, 0
	s_and_b64 vcc, exec, s[70:71]
	s_mul_i32 s12, s34, 0xa000
	s_cbranch_vccnz .LBB0_1107
	s_add_u32 s84, s86, s68
	s_addc_u32 s85, s87, s69
	s_add_i32 s13, s12, 0xffff6000
	s_cmp_lg_u32 s34, 0
	s_cselect_b32 s13, s13, 0x14000
	s_add_i32 s13, s13, s97
	s_mov_b32 m0, s13
	s_nop 0
	global_load_lds_dwordx4 v200, s[84:85]
	s_add_i32 m0, s13, 0x1f80
	s_nop 0
	global_load_lds_dwordx4 v200, s[84:85] offset:128
	s_add_i32 m0, s13, 0x3f00
	s_nop 0
	global_load_lds_dwordx4 v200, s[84:85] offset:256
	s_add_u32 s84, s86, s66
	s_addc_u32 s85, s87, s67
	s_add_i32 m0, s13, 0x6000
	s_nop 0
	global_load_lds_dwordx4 v202, s[84:85]
	s_add_i32 m0, s13, 0x7fc0
	s_nop 0
	global_load_lds_dwordx4 v202, s[84:85] offset:64
.LBB0_1107:
	s_cmp_gt_i32 s35, s95
	s_cbranch_scc1 .LBB0_1109
	s_add_i32 s12, s12, 0
	v_add_u32_e32 v113, s12, v204
	ds_read_b128 v[114:117], v113
	ds_read_b128 v[118:121], v113 offset:1024
	ds_read_b128 v[122:125], v113 offset:2048
	ds_read_b128 v[130:133], v113 offset:3072
	ds_read_b128 v[134:137], v113 offset:4096
	ds_read_b128 v[138:141], v113 offset:5120
	ds_read_b128 v[142:145], v113 offset:6144
	ds_read_b128 v[146:149], v113 offset:7168
	s_waitcnt lgkmcnt(4)
	v_mfma_f32_16x16x32_bf16 v[150:153], v[114:117], v[0:3], 0
	v_mfma_f32_16x16x32_bf16 v[114:117], v[114:117], v[24:27], 0
	v_mfma_f32_16x16x32_bf16 v[154:157], v[118:121], v[0:3], 0
	v_mfma_f32_16x16x32_bf16 v[118:121], v[118:121], v[24:27], 0
	v_mfma_f32_16x16x32_bf16 v[158:161], v[122:125], v[0:3], 0
	v_mfma_f32_16x16x32_bf16 v[122:125], v[122:125], v[24:27], 0
	v_mfma_f32_16x16x32_bf16 v[162:165], v[130:133], v[0:3], 0
	v_mfma_f32_16x16x32_bf16 v[130:133], v[130:133], v[24:27], 0
	ds_read_b128 v[166:169], v113 offset:8192
	ds_read_b128 v[170:173], v113 offset:9216
	ds_read_b128 v[174:177], v113 offset:10240
	ds_read_b128 v[178:181], v113 offset:11264
	s_waitcnt lgkmcnt(4)
	v_mfma_f32_16x16x32_bf16 v[150:153], v[134:137], v[4:7], v[150:153]
	v_mfma_f32_16x16x32_bf16 v[114:117], v[134:137], v[28:31], v[114:117]
	v_mfma_f32_16x16x32_bf16 v[134:137], v[138:141], v[4:7], v[154:157]
	v_mfma_f32_16x16x32_bf16 v[118:121], v[138:141], v[28:31], v[118:121]
	v_mfma_f32_16x16x32_bf16 v[138:141], v[142:145], v[4:7], v[158:161]
	v_mfma_f32_16x16x32_bf16 v[122:125], v[142:145], v[28:31], v[122:125]
	v_mfma_f32_16x16x32_bf16 v[142:145], v[146:149], v[4:7], v[162:165]
	v_mfma_f32_16x16x32_bf16 v[130:133], v[146:149], v[28:31], v[130:133]
	ds_read_b128 v[146:149], v113 offset:12288
	ds_read_b128 v[154:157], v113 offset:13312
	ds_read_b128 v[158:161], v113 offset:14336
	ds_read_b128 v[162:165], v113 offset:15360
	s_waitcnt lgkmcnt(4)
	v_mfma_f32_16x16x32_bf16 v[150:153], v[166:169], v[8:11], v[150:153]
	v_mfma_f32_16x16x32_bf16 v[114:117], v[166:169], v[32:35], v[114:117]
	v_mfma_f32_16x16x32_bf16 v[134:137], v[170:173], v[8:11], v[134:137]
	v_mfma_f32_16x16x32_bf16 v[118:121], v[170:173], v[32:35], v[118:121]
	v_mfma_f32_16x16x32_bf16 v[138:141], v[174:177], v[8:11], v[138:141]
	v_mfma_f32_16x16x32_bf16 v[122:125], v[174:177], v[32:35], v[122:125]
	v_mfma_f32_16x16x32_bf16 v[142:145], v[178:181], v[8:11], v[142:145]
	v_mfma_f32_16x16x32_bf16 v[130:133], v[178:181], v[32:35], v[130:133]
	ds_read_b128 v[166:169], v113 offset:16384
	ds_read_b128 v[170:173], v113 offset:17408
	ds_read_b128 v[174:177], v113 offset:18432
	ds_read_b128 v[178:181], v113 offset:19456
	s_waitcnt lgkmcnt(4)
	v_mfma_f32_16x16x32_bf16 v[150:153], v[146:149], v[12:15], v[150:153]
	v_mfma_f32_16x16x32_bf16 v[114:117], v[146:149], v[36:39], v[114:117]
	v_mfma_f32_16x16x32_bf16 v[134:137], v[154:157], v[12:15], v[134:137]
	v_mfma_f32_16x16x32_bf16 v[118:121], v[154:157], v[36:39], v[118:121]
	v_mfma_f32_16x16x32_bf16 v[138:141], v[158:161], v[12:15], v[138:141]
	v_mfma_f32_16x16x32_bf16 v[122:125], v[158:161], v[36:39], v[122:125]
	v_mfma_f32_16x16x32_bf16 v[142:145], v[162:165], v[12:15], v[142:145]
	v_mfma_f32_16x16x32_bf16 v[130:133], v[162:165], v[36:39], v[130:133]
	ds_read_b128 v[146:149], v113 offset:20480
	ds_read_b128 v[154:157], v113 offset:21504
	ds_read_b128 v[158:161], v113 offset:22528
	ds_read_b128 v[162:165], v113 offset:23552
	s_waitcnt lgkmcnt(4)
	v_mfma_f32_16x16x32_bf16 v[150:153], v[166:169], v[16:19], v[150:153]
	v_mfma_f32_16x16x32_bf16 v[114:117], v[166:169], v[40:43], v[114:117]
	v_mfma_f32_16x16x32_bf16 v[134:137], v[170:173], v[16:19], v[134:137]
	v_mfma_f32_16x16x32_bf16 v[118:121], v[170:173], v[40:43], v[118:121]
	v_mfma_f32_16x16x32_bf16 v[138:141], v[174:177], v[16:19], v[138:141]
	v_mfma_f32_16x16x32_bf16 v[122:125], v[174:177], v[40:43], v[122:125]
	v_mfma_f32_16x16x32_bf16 v[142:145], v[178:181], v[16:19], v[142:145]
	v_mfma_f32_16x16x32_bf16 v[130:133], v[178:181], v[40:43], v[130:133]
	s_waitcnt lgkmcnt(0)
; __device__ __forceinline__ float xor16_max(float v) { float a = v, b = v; swap16(a, b); return fmaxf(a, b); }
; __device__ __forceinline__ float xor32_max(float v) { float a = v, b = v; swap32(a, b); return fmaxf(a, b); }
; template <int DQK, int QF>
; __device__ __forceinline__ void attn_unit_dma(LAS unsigned char* lds, const bf16_t* Qp, int ldq, const bf16_t* Kp, int ldk, const bf16_t* VTp, int ldvt, bf16_t* Op, int ldo, int nkt, int wave_last, const float* qgam, float qscale) {
;     ...
;                 }
;             }
;             bf16x8 pb[QF][2];
; #pragma unroll
;             for (int qf = 0; qf < QF; ++qf) {
;                 float mx = st[qf][0][0];
; #pragma unroll
;                 for (int m = 0; m < 4; ++m)
; #pragma unroll
;                     for (int j = 0; j < 4; ++j) mx = fmaxf(mx, st[qf][m][j]);
;                 mx = xor16_max(mx); mx = xor32_max(mx);
;                 const float mnew = fmaxf(mrun[qf], mx), alpha = __builtin_amdgcn_exp2f(mrun[qf] - mnew);
;                 mrun[qf] = mnew;
;                 float ps = 0.f; float p[4][4];
; #pragma unroll
;                 for (int m = 0; m < 4; ++m)
; #pragma unroll
;                     for (int j = 0; j < 4; ++j) { p[m][j] = __builtin_amdgcn_exp2f(st[qf][m][j] - mnew); ps += p[m][j]; }
;                 lrun[qf] = lrun[qf] * alpha + ps;
; #pragma unroll
;                 for (int mv = 0; mv < 8; ++mv) o[qf][mv] = o[qf][mv] * alpha;
	v_mfma_f32_16x16x32_bf16 v[150:153], v[146:149], v[20:23], v[150:153]
	v_mfma_f32_16x16x32_bf16 v[146:149], v[146:149], v[44:47], v[114:117]
	v_mfma_f32_16x16x32_bf16 v[114:117], v[154:157], v[20:23], v[134:137]
	s_nop 5
	v_max_f32_e32 v113, v151, v151
	v_max_f32_e32 v126, v150, v150
	v_max_f32_e32 v113, v126, v113
	v_mfma_f32_16x16x32_bf16 v[134:137], v[154:157], v[44:47], v[118:121]
	v_max3_f32 v113, v113, v152, v153
	v_max3_f32 v113, v113, v114, v115
	v_max3_f32 v113, v113, v116, v117
	v_mfma_f32_16x16x32_bf16 v[118:121], v[158:161], v[20:23], v[138:141]
	v_mfma_f32_16x16x32_bf16 v[138:141], v[158:161], v[44:47], v[122:125]
	v_mfma_f32_16x16x32_bf16 v[122:125], v[162:165], v[20:23], v[142:145]
	s_nop 5
	v_max3_f32 v113, v113, v118, v119
	v_max3_f32 v113, v113, v120, v121
	v_mfma_f32_16x16x32_bf16 v[130:133], v[162:165], v[44:47], v[130:133]
	v_max3_f32 v113, v113, v122, v123
	v_max3_f32 v113, v113, v124, v125
	v_mov_b32_e32 v126, v113
	s_nop 1
	v_permlane16_swap_b32 v113, v126
	s_nop 0
	v_max_f32_e32 v126, v126, v126
	v_max_f32_e32 v113, v113, v113
	v_max_f32_e32 v113, v113, v126
	v_mov_b32_e32 v126, v113
	s_nop 1
	v_permlane32_swap_b32 v113, v126
	s_nop 0
	v_max3_f32 v220, v112, v113, v126
	v_sub_f32_e32 v113, v150, v220
	v_exp_f32_e32 v143, v113
	v_sub_f32_e32 v113, v151, v220
	v_sub_f32_e32 v112, v112, v220
	v_exp_f32_e32 v145, v113
	v_sub_f32_e32 v113, v152, v220
	v_exp_f32_e32 v151, v113
	v_sub_f32_e32 v113, v153, v220
	v_exp_f32_e32 v178, v112
	v_exp_f32_e32 v153, v113
	v_sub_f32_e32 v113, v114, v220
	v_exp_f32_e32 v155, v113
	v_sub_f32_e32 v113, v115, v220
	v_exp_f32_e32 v157, v113
	v_sub_f32_e32 v113, v116, v220
	v_exp_f32_e32 v159, v113
	v_sub_f32_e32 v113, v117, v220
	v_pk_mul_f32 v[116:117], v[92:93], v[178:179] op_sel_hi:[1,0]
	v_pk_mul_f32 v[92:93], v[104:105], v[178:179] op_sel_hi:[1,0]
	v_max_f32_e32 v104, v147, v147
	v_max_f32_e32 v105, v146, v146
	v_max_f32_e32 v104, v105, v104
	v_max3_f32 v104, v104, v148, v149
	v_max3_f32 v104, v104, v134, v135
	v_max3_f32 v104, v104, v136, v137
	v_max3_f32 v104, v104, v138, v139
	v_max3_f32 v104, v104, v140, v141
	v_max3_f32 v104, v104, v130, v131
	v_max3_f32 v104, v104, v132, v133
	v_mov_b32_e32 v105, v104
	s_nop 1
	v_permlane16_swap_b32 v104, v105
	v_exp_f32_e32 v161, v113
	v_max_f32_e32 v105, v105, v105
	v_max_f32_e32 v104, v104, v104
	v_max_f32_e32 v104, v104, v105
	v_mov_b32_e32 v105, v104
	s_nop 1
	v_permlane32_swap_b32 v104, v105
	v_sub_f32_e32 v113, v118, v220
	v_max3_f32 v221, v128, v104, v105
	v_sub_f32_e32 v104, v146, v221
	v_exp_f32_e32 v142, v104
	v_sub_f32_e32 v104, v147, v221
	v_exp_f32_e32 v144, v104
	v_sub_f32_e32 v104, v148, v221
	v_exp_f32_e32 v150, v104
	v_sub_f32_e32 v104, v149, v221
	v_exp_f32_e32 v152, v104
	v_sub_f32_e32 v104, v134, v221
	v_exp_f32_e32 v154, v104
	v_sub_f32_e32 v104, v135, v221
	v_exp_f32_e32 v156, v104
	v_sub_f32_e32 v104, v136, v221
	v_exp_f32_e32 v158, v104
	v_pk_add_f32 v[104:105], v[142:143], 0 op_sel_hi:[1,0]
	v_exp_f32_e32 v163, v113
	v_pk_add_f32 v[104:105], v[144:145], v[104:105]
	v_sub_f32_e32 v113, v119, v220
	v_pk_mul_f32 v[118:119], v[94:95], v[178:179] op_sel_hi:[1,0]
	v_pk_mul_f32 v[94:95], v[106:107], v[178:179] op_sel_hi:[1,0]
	v_pk_add_f32 v[104:105], v[150:151], v[104:105]
	v_sub_f32_e32 v107, v137, v221
	v_pk_add_f32 v[104:105], v[152:153], v[104:105]
	v_exp_f32_e32 v160, v107
	v_sub_f32_e32 v107, v138, v221
	v_pk_add_f32 v[104:105], v[154:155], v[104:105]
	v_exp_f32_e32 v162, v107
	v_sub_f32_e32 v107, v139, v221
	v_exp_f32_e32 v165, v113
	v_sub_f32_e32 v113, v120, v220
	v_pk_add_f32 v[104:105], v[156:157], v[104:105]
	v_exp_f32_e32 v164, v107
	v_sub_f32_e32 v107, v140, v221
	v_exp_f32_e32 v167, v113
	v_sub_f32_e32 v113, v121, v220
	v_pk_add_f32 v[104:105], v[158:159], v[104:105]
	v_exp_f32_e32 v166, v107
	v_sub_f32_e32 v107, v141, v221
	v_exp_f32_e32 v169, v113
	v_sub_f32_e32 v113, v122, v220
	v_exp_f32_e32 v168, v107
	v_sub_f32_e32 v107, v130, v221
	v_pk_add_f32 v[104:105], v[160:161], v[104:105]
	v_exp_f32_e32 v171, v113
	v_sub_f32_e32 v113, v123, v220
	v_exp_f32_e32 v170, v107
	v_sub_f32_e32 v107, v131, v221
	v_pk_add_f32 v[104:105], v[162:163], v[104:105]
	v_exp_f32_e32 v173, v113
	v_sub_f32_e32 v113, v124, v220
	v_exp_f32_e32 v172, v107
	v_sub_f32_e32 v107, v132, v221
	v_pk_add_f32 v[104:105], v[164:165], v[104:105]
	v_exp_f32_e32 v175, v113
	v_sub_f32_e32 v113, v125, v220
	v_exp_f32_e32 v174, v107
	v_sub_f32_e32 v107, v133, v221
	v_pk_add_f32 v[104:105], v[166:167], v[104:105]
	v_exp_f32_e32 v177, v113
	v_sub_f32_e32 v106, v128, v221
	v_exp_f32_e32 v176, v107
	v_pk_add_f32 v[104:105], v[168:169], v[104:105]
	v_exp_f32_e32 v136, v106
	v_pk_add_f32 v[104:105], v[170:171], v[104:105]
	v_mov_b32_e32 v137, v178
	v_pk_add_f32 v[104:105], v[172:173], v[104:105]
	v_pk_mul_f32 v[126:127], v[98:99], v[178:179] op_sel_hi:[1,0]
	v_pk_add_f32 v[104:105], v[174:175], v[104:105]
	v_pk_mul_f32 v[124:125], v[96:97], v[178:179] op_sel_hi:[1,0]
	v_pk_add_f32 v[104:105], v[176:177], v[104:105]
	v_pk_mul_f32 v[98:99], v[90:91], v[178:179] op_sel_hi:[1,0]
	v_pk_mul_f32 v[96:97], v[88:89], v[178:179] op_sel_hi:[1,0]
	v_pk_mul_f32 v[90:91], v[110:111], v[178:179] op_sel_hi:[1,0]
	v_pk_mul_f32 v[88:89], v[108:109], v[178:179] op_sel_hi:[1,0]
	v_pk_fma_f32 v[206:207], v[206:207], v[136:137], v[104:105]
	v_pk_mul_f32 v[134:135], v[70:71], v[136:137] op_sel_hi:[1,0]
	v_pk_mul_f32 v[132:133], v[68:69], v[136:137] op_sel_hi:[1,0]
	v_pk_mul_f32 v[130:131], v[66:67], v[136:137] op_sel_hi:[1,0]
	v_pk_mul_f32 v[128:129], v[64:65], v[136:137] op_sel_hi:[1,0]
	v_pk_mul_f32 v[110:111], v[62:63], v[136:137] op_sel_hi:[1,0]
; __device__ __forceinline__ unsigned pk2(float lo, float hi) { f32x2_t v = {lo, hi}; bf16x2_t b = __builtin_convertvector(v, bf16x2_t); return __builtin_bit_cast(unsigned, b); }
; #define AT_VLOAD(buf_, grp_) do { _Pragma("unroll") for (int i = 0; i < 4; ++i) { const int s2_ = (grp_) >> 1, mv_ = ((grp_) & 1) * 4 + i; \
;                     const LAS unsigned char* vp = vb + (16 * mv_ + fr) * VROW + (32 * s2_ + 4 * fq) * 2; \
;                     vr[buf_][i][0] = *(const LAS u32x2*)vp; vr[buf_][i][1] = *(const LAS u32x2*)(vp + 32); } } while (0)
; template <int DQK, int QF>
; __device__ __forceinline__ void attn_unit_dma(LAS unsigned char* lds, const bf16_t* Qp, int ldq, const bf16_t* Kp, int ldk, const bf16_t* VTp, int ldvt, bf16_t* Op, int ldo, int nkt, int wave_last, const float* qgam, float qscale) {
;     ...
;                 lrun[qf] = lrun[qf] * alpha + ps;
; #pragma unroll
;                 for (int mv = 0; mv < 8; ++mv) o[qf][mv] = o[qf][mv] * alpha;
; #pragma unroll
;                 for (int s2 = 0; s2 < 2; ++s2) {
;                     u32x4 w; w.x = pk2(p[2 * s2][0], p[2 * s2][1]); w.y = pk2(p[2 * s2][2], p[2 * s2][3]); w.z = pk2(p[2 * s2 + 1][0], p[2 * s2 + 1][1]); w.w = pk2(p[2 * s2 + 1][2], p[2 * s2 + 1][3]);
;                     pb[qf][s2] = __builtin_bit_cast(bf16x8, w);
;                 }
;             }
;             {
;                 u32x2 vr[2][4][2];
;     ...
;                 AT_VLOAD(0, 0);
; #pragma unroll
;                 for (int grp = 0; grp < 4; ++grp) {
;                     if (grp + 1 < 4) AT_VLOAD((grp + 1) & 1, grp + 1);
;                     __builtin_amdgcn_sched_group_barrier(0x100, 8, 0);
;                     __builtin_amdgcn_sched_group_barrier(0x008, 4 * QF, 0);
; #pragma unroll
;                     for (int i = 0; i < 4; ++i) {
;                         const int s2 = grp >> 1, mv = (grp & 1) * 4 + i;
;                         u32x4 vv; vv.x = vr[grp & 1][i][0].x; vv.y = vr[grp & 1][i][0].y; vv.z = vr[grp & 1][i][1].x; vv.w = vr[grp & 1][i][1].y;
;                         const bf16x8 vf = __builtin_bit_cast(bf16x8, vv);
; #pragma unroll
;                         for (int qf = 0; qf < QF; ++qf) o[qf][mv] = __builtin_amdgcn_mfma_f32_16x16x32_bf16(vf, pb[qf][s2], o[qf][mv], 0, 0, 0);
;                     }
;                 }
	v_pk_mul_f32 v[108:109], v[60:61], v[136:137] op_sel_hi:[1,0]
	v_pk_mul_f32 v[106:107], v[58:59], v[136:137] op_sel_hi:[1,0]
	v_pk_mul_f32 v[104:105], v[56:57], v[136:137] op_sel_hi:[1,0]
	v_pk_mul_f32 v[70:71], v[74:75], v[136:137] op_sel_hi:[1,0]
	v_pk_mul_f32 v[68:69], v[72:73], v[136:137] op_sel_hi:[1,0]
	v_pk_mul_f32 v[66:67], v[78:79], v[136:137] op_sel_hi:[1,0]
	v_pk_mul_f32 v[64:65], v[76:77], v[136:137] op_sel_hi:[1,0]
	v_pk_mul_f32 v[62:63], v[82:83], v[136:137] op_sel_hi:[1,0]
	v_pk_mul_f32 v[60:61], v[80:81], v[136:137] op_sel_hi:[1,0]
	v_pk_mul_f32 v[58:59], v[54:55], v[136:137] op_sel_hi:[1,0]
	v_pk_mul_f32 v[56:57], v[52:53], v[136:137] op_sel_hi:[1,0]
	v_add_u32_e32 v222, s12, v204
	v_pk_mul_f32 v[112:113], v[84:85], v[178:179] op_sel_hi:[1,0]
	v_pk_mul_f32 v[84:85], v[48:49], v[178:179] op_sel_hi:[1,0]
	v_cvt_pk_bf16_f32 v48, v163, v165
	v_cvt_pk_bf16_f32 v49, v167, v169
	v_cvt_pk_bf16_f32 v52, v162, v164
	v_cvt_pk_bf16_f32 v53, v166, v168
	v_pk_mul_f32 v[122:123], v[102:103], v[178:179] op_sel_hi:[1,0]
	v_pk_mul_f32 v[120:121], v[100:101], v[178:179] op_sel_hi:[1,0]
	v_cvt_pk_bf16_f32 v100, v143, v145
	v_cvt_pk_bf16_f32 v101, v151, v153
	v_cvt_pk_bf16_f32 v102, v155, v157
	v_cvt_pk_bf16_f32 v103, v159, v161
	v_cvt_pk_bf16_f32 v72, v142, v144
	v_cvt_pk_bf16_f32 v73, v150, v152
	v_cvt_pk_bf16_f32 v74, v154, v156
	v_cvt_pk_bf16_f32 v75, v158, v160
	ds_read_b128 v[76:79], v222 offset:24576
	ds_read_b128 v[80:83], v222 offset:25600
	ds_read_b128 v[156:159], v222 offset:26624
	ds_read_b128 v[160:163], v222 offset:27648
	ds_read_b128 v[140:143], v222 offset:28672
	ds_read_b128 v[144:147], v222 offset:29696
	ds_read_b128 v[148:151], v222 offset:30720
	ds_read_b128 v[152:155], v222 offset:31744
	v_pk_mul_f32 v[114:115], v[86:87], v[178:179] op_sel_hi:[1,0]
	v_pk_mul_f32 v[86:87], v[50:51], v[178:179] op_sel_hi:[1,0]
	v_cvt_pk_bf16_f32 v50, v171, v173
	v_cvt_pk_bf16_f32 v51, v175, v177
	v_cvt_pk_bf16_f32 v54, v170, v172
	v_cvt_pk_bf16_f32 v55, v174, v176
	s_waitcnt lgkmcnt(4)
	v_mfma_f32_16x16x32_bf16 v[136:139], v[76:79], v[100:103], v[124:127]
	v_mfma_f32_16x16x32_bf16 v[132:135], v[76:79], v[72:75], v[132:135]
	v_mfma_f32_16x16x32_bf16 v[120:123], v[80:83], v[100:103], v[120:123]
	v_mfma_f32_16x16x32_bf16 v[124:127], v[80:83], v[72:75], v[128:131]
	v_mfma_f32_16x16x32_bf16 v[116:119], v[156:159], v[100:103], v[116:119]
	v_mfma_f32_16x16x32_bf16 v[108:111], v[156:159], v[72:75], v[108:111]
	v_mfma_f32_16x16x32_bf16 v[76:79], v[160:163], v[100:103], v[112:115]
	v_mfma_f32_16x16x32_bf16 v[80:83], v[160:163], v[72:75], v[104:107]
	ds_read_b128 v[180:183], v222 offset:32768
	ds_read_b128 v[176:179], v222 offset:33792
	ds_read_b128 v[172:175], v222 offset:34816
	ds_read_b128 v[168:171], v222 offset:35840
	ds_read_b128 v[226:229], v222 offset:38912
	s_waitcnt lgkmcnt(5)
	v_mfma_f32_16x16x32_bf16 v[164:167], v[140:143], v[100:103], v[96:99]
	v_mfma_f32_16x16x32_bf16 v[160:163], v[140:143], v[72:75], v[68:71]
	v_mfma_f32_16x16x32_bf16 v[104:107], v[144:147], v[100:103], v[92:95]
	v_mfma_f32_16x16x32_bf16 v[156:159], v[144:147], v[72:75], v[64:67]
	v_mfma_f32_16x16x32_bf16 v[144:147], v[148:151], v[100:103], v[88:91]
	v_mfma_f32_16x16x32_bf16 v[140:143], v[148:151], v[72:75], v[60:63]
	v_mfma_f32_16x16x32_bf16 v[112:115], v[152:155], v[100:103], v[84:87]
	v_mfma_f32_16x16x32_bf16 v[128:131], v[152:155], v[72:75], v[56:59]
	ds_read_b128 v[72:75], v222 offset:36864
	ds_read_b128 v[152:155], v222 offset:37888
	ds_read_b128 v[148:151], v222 offset:39936
	s_waitcnt lgkmcnt(4)
	v_mfma_f32_16x16x32_bf16 v[96:99], v[180:183], v[48:51], v[136:139]
	v_mfma_f32_16x16x32_bf16 v[68:71], v[180:183], v[52:55], v[132:135]
	v_mfma_f32_16x16x32_bf16 v[100:103], v[176:179], v[48:51], v[120:123]
	v_mfma_f32_16x16x32_bf16 v[64:67], v[176:179], v[52:55], v[124:127]
	v_mfma_f32_16x16x32_bf16 v[92:95], v[172:175], v[48:51], v[116:119]
	v_mfma_f32_16x16x32_bf16 v[60:63], v[172:175], v[52:55], v[108:111]
	v_mfma_f32_16x16x32_bf16 v[84:87], v[168:171], v[48:51], v[76:79]
	v_mfma_f32_16x16x32_bf16 v[56:59], v[168:171], v[52:55], v[80:83]
	s_waitcnt lgkmcnt(0)
	v_mfma_f32_16x16x32_bf16 v[88:91], v[72:75], v[48:51], v[164:167]
	v_mfma_f32_16x16x32_bf16 v[72:75], v[72:75], v[52:55], v[160:163]
	v_mfma_f32_16x16x32_bf16 v[104:107], v[152:155], v[48:51], v[104:107]
	v_mfma_f32_16x16x32_bf16 v[76:79], v[152:155], v[52:55], v[156:159]
	v_mfma_f32_16x16x32_bf16 v[108:111], v[226:229], v[48:51], v[144:147]
	v_mfma_f32_16x16x32_bf16 v[80:83], v[226:229], v[52:55], v[140:143]
	v_mfma_f32_16x16x32_bf16 v[48:51], v[148:151], v[48:51], v[112:115]
	v_mfma_f32_16x16x32_bf16 v[52:55], v[148:151], v[52:55], v[128:131]
	s_nop 1
	v_mov_b32_e32 v112, v220
	v_mov_b32_e32 v128, v221
; #define AT_DMA(t_, slot_) do { _Pragma("unroll") for (int j = 0; j < NJ; ++j) { const int g = wid + 8 * j; if (g < NIT) { \
;         const bf16_t* src_ = (g < NKI) ? (Kp + (size_t)(t_) * 64 * ldk + goff[j]) : (VTp + (size_t)(t_) * 64 + goff[j]); \
;         __builtin_amdgcn_global_load_lds((const unsigned*)src_, (LAS unsigned*)(lds + (slot_) * BUF + g * 1024), 16, 0, 0); } } } while (0)
; #define AT_WAIT_KEEP1() do { if (full) asm volatile("s_waitcnt vmcnt(%0)" :: "n"(NJ) : "memory"); else asm volatile("s_waitcnt vmcnt(%0)" :: "n"(NJ - 1) : "memory"); } while (0)
; #define AT_WAIT_ALL() asm volatile("s_waitcnt vmcnt(0)" ::: "memory")
; template <int DQK, int QF>
; __device__ __forceinline__ void attn_unit_dma(LAS unsigned char* lds, const bf16_t* Qp, int ldq, const bf16_t* Kp, int ldk, const bf16_t* VTp, int ldvt, bf16_t* Op, int ldo, int nkt, int wave_last, const float* qgam, float qscale) {
;     ...
;     asm volatile("s_waitcnt vmcnt(0)" ::: "memory");
;     AT_DMA(0, 0);
;     if (nkt > 1) { AT_DMA(1, 1); AT_WAIT_KEEP1(); } else AT_WAIT_ALL();
;     ...
;         asm volatile("s_waitcnt lgkmcnt(0)" ::: "memory");
;         if (t + 2 < nkt) AT_WAIT_KEEP1(); else AT_WAIT_ALL();
;         __builtin_amdgcn_s_barrier();
;         slot = (slot == 2) ? 0 : slot + 1;
.LBB0_1109:
	s_waitcnt lgkmcnt(0)
	s_and_b64 vcc, exec, s[70:71]
	s_cbranch_vccz .Lmy_att_keep1
	s_waitcnt vmcnt(0)
	s_branch .LBB0_1098
.Lmy_att_keep1:
	s_waitcnt vmcnt(5)
	s_branch .LBB0_1098
.LBB0_1121:
	s_lshl_b32 s12, s16, 10
	s_add_i32 m0, s12, 0
	s_and_b64 s[12:13], s[44:45], exec
	s_cselect_b32 s12, s83, s27
	s_cselect_b32 s13, s82, s26
	v_mov_b32_e32 v50, s13
	v_mov_b32_e32 v51, s12
	v_mov_b32_e32 v201, v189
	v_lshl_add_u64 v[50:51], v[200:201], 1, v[50:51]
	s_cmpk_lt_u32 s33, 0x8c0
	s_cselect_b64 s[54:55], -1, 0
	s_cmpk_gt_u32 s33, 0x8bf
	s_cbranch_scc1 .LBB0_1078
.LBB0_1122:
	s_lshl_b32 s12, s17, 10
	s_add_i32 m0, s12, 0
	s_and_b64 s[12:13], exec, s[46:47]
	s_cselect_b32 s12, s83, s27
	s_cselect_b32 s13, s82, s26
	v_mov_b32_e32 v50, s13
	v_mov_b32_e32 v51, s12
	v_mov_b32_e32 v203, v189
	v_lshl_add_u64 v[50:51], v[202:203], 1, v[50:51]
	s_cmpk_lt_u32 s33, 0x6c0
	s_cselect_b64 s[56:57], -1, 0
	s_cmpk_gt_u32 s33, 0x6bf
	s_cbranch_scc1 .LBB0_1079
.LBB0_1123:
	s_lshl_b32 s12, s22, 10
	s_add_i32 m0, s12, 0
	s_and_b64 s[12:13], exec, s[48:49]
	s_cselect_b32 s12, s83, s27
	s_cselect_b32 s13, s82, s26
	v_mov_b32_e32 v50, s13
	v_mov_b32_e32 v51, s12
	v_mov_b32_e32 v205, v189
	v_lshl_add_u64 v[50:51], v[204:205], 1, v[50:51]
	s_cmpk_lt_u32 s33, 0x4c0
	s_cselect_b64 s[58:59], -1, 0
	s_cmpk_gt_u32 s33, 0x4bf
	s_cbranch_scc0 .LBB0_1080
	s_branch .LBB0_1081
.LBB0_1124:
	s_lshl_b32 s33, s16, 10
	s_add_i32 s33, s33, 0
	s_add_i32 m0, s33, 0xac00
	s_and_b64 s[66:67], s[44:45], exec
	s_cselect_b32 s33, s93, s91
	s_cselect_b32 s66, s92, s90
	v_mov_b32_e32 v58, s66
	v_mov_b32_e32 v59, s33
	v_mov_b32_e32 v201, v189
	v_lshl_add_u64 v[58:59], v[200:201], 1, v[58:59]
	s_andn2_b64 vcc, exec, s[54:55]
	s_cbranch_vccnz .LBB0_1090
.LBB0_1125:
	s_lshl_b32 s33, s17, 10
	s_add_i32 s33, s33, 0
	s_add_i32 m0, s33, 0xac00
	s_and_b64 s[66:67], exec, s[46:47]
	s_cselect_b32 s33, s93, s91
	s_cselect_b32 s66, s92, s90
	v_mov_b32_e32 v58, s66
	v_mov_b32_e32 v59, s33
	v_mov_b32_e32 v203, v189
	v_lshl_add_u64 v[58:59], v[202:203], 1, v[58:59]
	s_andn2_b64 vcc, exec, s[56:57]
	s_cbranch_vccnz .LBB0_1091
.LBB0_1126:
	s_lshl_b32 s33, s22, 10
	s_add_i32 s33, s33, 0
	s_add_i32 m0, s33, 0xac00
	s_and_b64 s[66:67], exec, s[48:49]
	s_cselect_b32 s33, s93, s91
	s_cselect_b32 s66, s92, s90
	v_mov_b32_e32 v58, s66
	v_mov_b32_e32 v59, s33
	v_mov_b32_e32 v205, v189
	v_lshl_add_u64 v[58:59], v[204:205], 1, v[58:59]
	s_andn2_b64 vcc, exec, s[58:59]
	s_cbranch_vccnz .LBB0_1092
.LBB0_1127:
	s_lshl_b32 s33, s23, 10
	s_add_i32 s33, s33, 0
	s_add_i32 m0, s33, 0xac00
	s_and_b64 s[66:67], exec, s[50:51]
	s_cselect_b32 s67, s93, s91
	s_cselect_b32 s66, s92, s90
	v_lshlrev_b32_e32 v51, 1, v48
	s_andn2_b64 vcc, exec, s[60:61]
	s_cbranch_vccnz .LBB0_1093
.LBB0_1128:
	s_lshl_b32 s33, s34, 10
	v_mov_b32_e32 v53, v189
	s_add_i32 s33, s33, 0
	v_lshl_add_u64 v[52:53], v[52:53], 1, s[26:27]
	s_add_i32 m0, s33, 0xac00
	v_lshl_add_u64 v[52:53], v[52:53], 0, s[4:5]
	s_mov_b64 s[66:67], -1
	s_and_b64 vcc, exec, s[64:65]
	s_cbranch_vccz .LBB0_1094
